# conv_mix loop two iterations per trip (both load sets in flight) added to wave-offset mixer ordering + batched pool classes 0-1
# baseline (speedup 1.0000x reference)
.LBB0_287:
	s_andn2_b64 vcc, exec, s[8:9]
	s_cbranch_vccnz .LBB0_292
	s_and_saveexec_b64 s[8:9], s[36:37]
	v_readlane_b32 s36, v252, 17
	v_readlane_b32 s40, v252, 21
	v_readlane_b32 s41, v252, 22
	v_readlane_b32 s37, v252, 18
	v_readlane_b32 s38, v252, 19
	v_readlane_b32 s39, v252, 20
	v_readlane_b32 s42, v252, 23
	v_readlane_b32 s43, v252, 24
	v_readlane_b32 s44, v252, 25
	v_readlane_b32 s45, v252, 26
	v_readlane_b32 s46, v252, 27
	v_readlane_b32 s47, v252, 28
	v_readlane_b32 s48, v252, 29
	v_readlane_b32 s49, v252, 30
	v_readlane_b32 s50, v252, 31
	v_readlane_b32 s51, v252, 32
	s_cbranch_execz .LBB0_291
	s_mov_b64 s[12:13], s[40:41]
	v_lshlrev_b32_e32 v0, 3, v25
	s_lshl_b32 s6, s98, 3
	s_mov_b64 s[10:11], 0
	s_cmp_lg_u32 s76, 0x20000
	s_cbranch_scc1 .Lconv_orig
.LBB0_290:
	v_mul_hi_i32 v1, v25, s84
	v_lshrrev_b32_e32 v4, 31, v1
	v_ashrrev_i32_e32 v1, 4, v1
	v_mov_b64_e32 v[2:3], s[72:73]
	v_add_u32_e32 v4, v1, v4
	v_mad_i64_i32 v[2:3], s[0:1], v4, s85, v[2:3]
	v_add_u32_e32 v25, s98, v25
	v_and_b32_e32 v1, 0x1fff, v4
	s_movk_i32 s0, 0xfd00
	v_cmp_lt_i32_e32 vcc, s99, v25
	v_mad_u64_u32 v[6:7], s[0:1], v4, s0, v[0:1]
	s_or_b64 s[10:11], vcc, s[10:11]
	v_cmp_gt_u32_e32 vcc, 2, v1
	v_cmp_eq_u32_e64 s[0:1], 0, v1
	v_mov_b32_e32 v1, 0xffffe400
	v_ashrrev_i32_e32 v7, 31, v6
	v_cndmask_b32_e64 v22, v1, 0, vcc
	v_mov_b32_e32 v1, 0xfffff200
	v_cndmask_b32_e64 v39, -1, 0, s[0:1]
	v_lshl_add_u64 v[20:21], v[6:7], 2, s[12:13]
	v_cndmask_b32_e64 v38, v1, 0, s[0:1]
	v_cndmask_b32_e64 v46, 1.0, 0, s[0:1]
	s_mov_b64 s[0:1], 0x1800
	v_ashrrev_i32_e32 v5, 31, v4
	v_lshlrev_b64 v[18:19], 1, v[6:7]
	v_lshl_add_u64 v[34:35], v[20:21], 0, s[0:1]
	s_movk_i32 s0, 0x1000
	v_cndmask_b32_e64 v23, -1, 0, vcc
	v_lshlrev_b64 v[4:5], 11, v[4:5]
	v_cndmask_b32_e64 v24, 1.0, 0, vcc
	v_lshl_add_u64 v[40:41], v[2:3], 0, v[18:19]
	v_add_co_u32_e32 v30, vcc, s0, v20
	v_lshl_add_u64 v[26:27], s[66:67], 0, v[4:5]
	global_load_dwordx4 v[2:5], v[20:21], off offset:16
	global_load_dwordx4 v[6:9], v[20:21], off
	global_load_dwordx4 v[10:13], v[20:21], off offset:3088
	global_load_dwordx4 v[14:17], v[20:21], off offset:3072
	v_addc_co_u32_e32 v31, vcc, 0, v21, vcc
	v_lshl_add_u64 v[22:23], v[40:41], 0, v[22:23]
	v_lshl_add_u64 v[42:43], v[40:41], 0, v[38:39]
	v_lshl_add_u64 v[48:49], v[26:27], 0, v[18:19]
	global_load_dwordx4 v[18:21], v[40:41], off
	global_load_dwordx4 v[26:29], v[40:41], off offset:1536
	s_nop 0
	global_load_dwordx4 v[30:33], v[30:31], off offset:2048
	s_nop 0
	global_load_dwordx4 v[34:37], v[34:35], off offset:16
	s_nop 0
	global_load_dwordx4 v[38:41], v[22:23], off offset:1536
	s_nop 0
	global_load_dwordx4 v[42:45], v[42:43], off offset:1536
	v_add_u32_e32 v0, s6, v0
	v_mov_b32_e32 v64, v0
	v_mul_hi_i32 v65, v25, s84
	v_lshrrev_b32_e32 v68, 31, v65
	v_ashrrev_i32_e32 v65, 4, v65
	v_mov_b64_e32 v[66:67], s[72:73]
	v_add_u32_e32 v68, v65, v68
	v_mad_i64_i32 v[66:67], s[0:1], v68, s85, v[66:67]
	v_add_u32_e32 v25, s98, v25
	v_and_b32_e32 v65, 0x1fff, v68
	s_movk_i32 s0, 0xfd00
	v_cmp_lt_i32_e32 vcc, s99, v25
	v_mad_u64_u32 v[70:71], s[0:1], v68, s0, v[64:65]
	s_or_b64 s[10:11], vcc, s[10:11]
	v_cmp_gt_u32_e32 vcc, 2, v65
	v_cmp_eq_u32_e64 s[0:1], 0, v65
	v_mov_b32_e32 v65, 0xffffe400
	v_ashrrev_i32_e32 v71, 31, v70
	v_cndmask_b32_e64 v86, v65, 0, vcc
	v_mov_b32_e32 v65, 0xfffff200
	v_cndmask_b32_e64 v103, -1, 0, s[0:1]
	v_lshl_add_u64 v[84:85], v[70:71], 2, s[12:13]
	v_cndmask_b32_e64 v102, v65, 0, s[0:1]
	v_cndmask_b32_e64 v110, 1.0, 0, s[0:1]
	s_mov_b64 s[0:1], 0x1800
	v_ashrrev_i32_e32 v69, 31, v68
	v_lshlrev_b64 v[82:83], 1, v[70:71]
	v_lshl_add_u64 v[98:99], v[84:85], 0, s[0:1]
	s_movk_i32 s0, 0x1000
	v_cndmask_b32_e64 v87, -1, 0, vcc
	v_lshlrev_b64 v[68:69], 11, v[68:69]
	v_cndmask_b32_e64 v88, 1.0, 0, vcc
	v_lshl_add_u64 v[104:105], v[66:67], 0, v[82:83]
	v_add_co_u32_e32 v94, vcc, s0, v84
	v_lshl_add_u64 v[90:91], s[66:67], 0, v[68:69]
	global_load_dwordx4 v[66:69], v[84:85], off offset:16
	global_load_dwordx4 v[70:73], v[84:85], off
	global_load_dwordx4 v[74:77], v[84:85], off offset:3088
	global_load_dwordx4 v[78:81], v[84:85], off offset:3072
	v_addc_co_u32_e32 v95, vcc, 0, v85, vcc
	v_lshl_add_u64 v[86:87], v[104:105], 0, v[86:87]
	v_lshl_add_u64 v[106:107], v[104:105], 0, v[102:103]
	v_lshl_add_u64 v[112:113], v[90:91], 0, v[82:83]
	global_load_dwordx4 v[82:85], v[104:105], off
	global_load_dwordx4 v[90:93], v[104:105], off offset:1536
	s_nop 0
	global_load_dwordx4 v[94:97], v[94:95], off offset:2048
	s_nop 0
	global_load_dwordx4 v[98:101], v[98:99], off offset:16
	s_nop 0
	global_load_dwordx4 v[102:105], v[86:87], off offset:1536
	s_nop 0
	global_load_dwordx4 v[106:109], v[106:107], off offset:1536
	v_add_u32_e32 v0, s6, v0
	s_waitcnt vmcnt(10)
	v_pk_mul_f32 v[4:5], v[4:5], v[24:25] op_sel_hi:[1,0]
	v_pk_mul_f32 v[8:9], v[8:9], v[24:25] op_sel_hi:[1,0]
	v_pk_mul_f32 v[12:13], v[46:47], v[12:13] op_sel_hi:[0,1]
	v_pk_mul_f32 v[16:17], v[46:47], v[16:17] op_sel_hi:[0,1]
	v_pk_mul_f32 v[14:15], v[46:47], v[14:15] op_sel_hi:[0,1]
	v_pk_mul_f32 v[10:11], v[46:47], v[10:11] op_sel_hi:[0,1]
	v_pk_mul_f32 v[6:7], v[6:7], v[24:25] op_sel_hi:[1,0]
	v_pk_mul_f32 v[2:3], v[2:3], v[24:25] op_sel_hi:[1,0]
	v_lshlrev_b32_e32 v1, 16, v18
	v_and_b32_e32 v24, 0xffff0000, v18
	v_lshlrev_b32_e32 v56, 16, v19
	v_and_b32_e32 v57, 0xffff0000, v19
	v_lshlrev_b32_e32 v58, 16, v20
	v_and_b32_e32 v59, 0xffff0000, v20
	v_lshlrev_b32_e32 v60, 16, v21
	v_and_b32_e32 v61, 0xffff0000, v21
	v_lshlrev_b32_e32 v19, 16, v26
	v_mov_b32_e32 v20, v14
	v_mov_b32_e32 v21, v30
	v_and_b32_e32 v23, 0xffff0000, v26
	v_mov_b32_e32 v30, v15
	v_lshlrev_b32_e32 v15, 16, v27
	v_mov_b32_e32 v46, v16
	v_mov_b32_e32 v47, v32
	v_and_b32_e32 v27, 0xffff0000, v27
	v_mov_b32_e32 v32, v17
	v_lshlrev_b32_e32 v17, 16, v28
	v_mov_b32_e32 v50, v10
	v_mov_b32_e32 v51, v34
	v_mov_b32_e32 v54, v12
	v_mov_b32_e32 v55, v36
	v_mov_b32_e32 v36, v13
	v_lshlrev_b32_e32 v12, 16, v38
	v_and_b32_e32 v13, 0xffff0000, v38
	v_lshlrev_b32_e32 v38, 16, v39
	v_and_b32_e32 v39, 0xffff0000, v39
	v_lshlrev_b32_e32 v62, 16, v40
	v_and_b32_e32 v40, 0xffff0000, v40
	v_lshlrev_b32_e32 v63, 16, v41
	v_and_b32_e32 v41, 0xffff0000, v41
	v_lshlrev_b32_e32 v18, 16, v42
	v_and_b32_e32 v22, 0xffff0000, v42
	v_lshlrev_b32_e32 v14, 16, v43
	v_and_b32_e32 v26, 0xffff0000, v43
	v_lshlrev_b32_e32 v16, 16, v44
	v_and_b32_e32 v53, 0xffff0000, v28
	v_mov_b32_e32 v34, v11
	v_lshlrev_b32_e32 v11, 16, v29
	v_and_b32_e32 v29, 0xffff0000, v29
	v_and_b32_e32 v52, 0xffff0000, v44
	v_lshlrev_b32_e32 v10, 16, v45
	v_and_b32_e32 v28, 0xffff0000, v45
	v_fma_f32 v42, v6, v12, 0
	v_fma_f32 v43, v7, v13, 0
	v_fma_f32 v38, v8, v38, 0
	v_fma_f32 v39, v9, v39, 0
	v_fma_f32 v44, v2, v62, 0
	v_fma_f32 v40, v3, v40, 0
	v_fma_f32 v45, v4, v63, 0
	v_fma_f32 v41, v5, v41, 0
	v_pk_mul_f32 v[2:3], v[20:21], v[18:19]
	v_pk_mul_f32 v[4:5], v[30:31], v[22:23]
	v_pk_mul_f32 v[6:7], v[46:47], v[14:15]
	v_pk_mul_f32 v[8:9], v[32:33], v[26:27]
	v_pk_mul_f32 v[12:13], v[50:51], v[16:17]
	v_pk_mul_f32 v[14:15], v[34:35], v[52:53]
	v_pk_mul_f32 v[10:11], v[54:55], v[10:11]
	v_pk_mul_f32 v[16:17], v[36:37], v[28:29]
	v_add_f32_e32 v2, v2, v42
	v_add_f32_e32 v4, v4, v43
	v_add_f32_e32 v6, v6, v38
	v_add_f32_e32 v8, v8, v39
	v_add_f32_e32 v12, v44, v12
	v_add_f32_e32 v14, v40, v14
	v_add_f32_e32 v10, v45, v10
	v_add_f32_e32 v16, v41, v16
	v_add_f32_e32 v2, v2, v3
	v_add_f32_e32 v3, v4, v5
	v_add_f32_e32 v4, v6, v7
	v_add_f32_e32 v5, v8, v9
	v_add_f32_e32 v6, v12, v13
	v_add_f32_e32 v7, v14, v15
	v_add_f32_e32 v8, v10, v11
	v_add_f32_e32 v9, v16, v17
	v_mul_f32_e32 v1, v2, v1
	v_mul_f32_e32 v2, v3, v24
	v_mul_f32_e32 v3, v4, v56
	v_mul_f32_e32 v4, v5, v57
	v_mul_f32_e32 v5, v6, v58
	v_mul_f32_e32 v6, v7, v59
	v_mul_f32_e32 v7, v8, v60
	v_mul_f32_e32 v8, v9, v61
	v_cvt_pk_bf16_f32 v2, v1, v2
	v_cvt_pk_bf16_f32 v3, v3, v4
	v_cvt_pk_bf16_f32 v4, v5, v6
	v_cvt_pk_bf16_f32 v5, v7, v8
	global_store_dwordx4 v[48:49], v[2:5], off
	s_waitcnt vmcnt(1)
	v_pk_mul_f32 v[68:69], v[68:69], v[88:89] op_sel_hi:[1,0]
	v_pk_mul_f32 v[72:73], v[72:73], v[88:89] op_sel_hi:[1,0]
	v_pk_mul_f32 v[76:77], v[110:111], v[76:77] op_sel_hi:[0,1]
	v_pk_mul_f32 v[80:81], v[110:111], v[80:81] op_sel_hi:[0,1]
	v_pk_mul_f32 v[78:79], v[110:111], v[78:79] op_sel_hi:[0,1]
	v_pk_mul_f32 v[74:75], v[110:111], v[74:75] op_sel_hi:[0,1]
	v_pk_mul_f32 v[70:71], v[70:71], v[88:89] op_sel_hi:[1,0]
	v_pk_mul_f32 v[66:67], v[66:67], v[88:89] op_sel_hi:[1,0]
	v_lshlrev_b32_e32 v65, 16, v82
	v_and_b32_e32 v88, 0xffff0000, v82
	v_lshlrev_b32_e32 v120, 16, v83
	v_and_b32_e32 v121, 0xffff0000, v83
	v_lshlrev_b32_e32 v122, 16, v84
	v_and_b32_e32 v123, 0xffff0000, v84
	v_lshlrev_b32_e32 v124, 16, v85
	v_and_b32_e32 v125, 0xffff0000, v85
	v_lshlrev_b32_e32 v83, 16, v90
	v_mov_b32_e32 v84, v78
	v_mov_b32_e32 v85, v94
	v_and_b32_e32 v87, 0xffff0000, v90
	v_mov_b32_e32 v94, v79
	v_lshlrev_b32_e32 v79, 16, v91
	v_mov_b32_e32 v110, v80
	v_mov_b32_e32 v111, v96
	v_and_b32_e32 v91, 0xffff0000, v91
	v_mov_b32_e32 v96, v81
	v_lshlrev_b32_e32 v81, 16, v92
	v_mov_b32_e32 v114, v74
	v_mov_b32_e32 v115, v98
	v_mov_b32_e32 v118, v76
	v_mov_b32_e32 v119, v100
	v_mov_b32_e32 v100, v77
	v_lshlrev_b32_e32 v76, 16, v102
	v_and_b32_e32 v77, 0xffff0000, v102
	v_lshlrev_b32_e32 v102, 16, v103
	v_and_b32_e32 v103, 0xffff0000, v103
	v_lshlrev_b32_e32 v126, 16, v104
	v_and_b32_e32 v104, 0xffff0000, v104
	v_lshlrev_b32_e32 v127, 16, v105
	v_and_b32_e32 v105, 0xffff0000, v105
	v_lshlrev_b32_e32 v82, 16, v106
	v_and_b32_e32 v86, 0xffff0000, v106
	v_lshlrev_b32_e32 v78, 16, v107
	v_and_b32_e32 v90, 0xffff0000, v107
	v_lshlrev_b32_e32 v80, 16, v108
	v_and_b32_e32 v117, 0xffff0000, v92
	v_mov_b32_e32 v98, v75
	v_lshlrev_b32_e32 v75, 16, v93
	v_and_b32_e32 v93, 0xffff0000, v93
	v_and_b32_e32 v116, 0xffff0000, v108
	v_lshlrev_b32_e32 v74, 16, v109
	v_and_b32_e32 v92, 0xffff0000, v109
	v_fma_f32 v106, v70, v76, 0
	v_fma_f32 v107, v71, v77, 0
	v_fma_f32 v102, v72, v102, 0
	v_fma_f32 v103, v73, v103, 0
	v_fma_f32 v108, v66, v126, 0
	v_fma_f32 v104, v67, v104, 0
	v_fma_f32 v109, v68, v127, 0
	v_fma_f32 v105, v69, v105, 0
	v_pk_mul_f32 v[66:67], v[84:85], v[82:83]
	v_pk_mul_f32 v[68:69], v[94:95], v[86:87]
	v_pk_mul_f32 v[70:71], v[110:111], v[78:79]
	v_pk_mul_f32 v[72:73], v[96:97], v[90:91]
	v_pk_mul_f32 v[76:77], v[114:115], v[80:81]
	v_pk_mul_f32 v[78:79], v[98:99], v[116:117]
	v_pk_mul_f32 v[74:75], v[118:119], v[74:75]
	v_pk_mul_f32 v[80:81], v[100:101], v[92:93]
	v_add_f32_e32 v66, v66, v106
	v_add_f32_e32 v68, v68, v107
	v_add_f32_e32 v70, v70, v102
	v_add_f32_e32 v72, v72, v103
	v_add_f32_e32 v76, v108, v76
	v_add_f32_e32 v78, v104, v78
	v_add_f32_e32 v74, v109, v74
	v_add_f32_e32 v80, v105, v80
	v_add_f32_e32 v66, v66, v67
	v_add_f32_e32 v67, v68, v69
	v_add_f32_e32 v68, v70, v71
	v_add_f32_e32 v69, v72, v73
	v_add_f32_e32 v70, v76, v77
	v_add_f32_e32 v71, v78, v79
	v_add_f32_e32 v72, v74, v75
	v_add_f32_e32 v73, v80, v81
	v_mul_f32_e32 v65, v66, v65
	v_mul_f32_e32 v66, v67, v88
	v_mul_f32_e32 v67, v68, v120
	v_mul_f32_e32 v68, v69, v121
	v_mul_f32_e32 v69, v70, v122
	v_mul_f32_e32 v70, v71, v123
	v_mul_f32_e32 v71, v72, v124
	v_mul_f32_e32 v72, v73, v125
	v_cvt_pk_bf16_f32 v66, v65, v66
	v_cvt_pk_bf16_f32 v67, v67, v68
	v_cvt_pk_bf16_f32 v68, v69, v70
	v_cvt_pk_bf16_f32 v69, v71, v72
	global_store_dwordx4 v[112:113], v[66:69], off
	s_andn2_b64 exec, exec, s[10:11]
	s_cbranch_execnz .LBB0_290
	s_branch .LBB0_291
